# P3: late-weight transposes run first on all 256 WGs (8 loads in flight), then the 32 GEMM WGs run alone
# speedup vs baseline: 1.0028x; 1.0028x over previous
.LBB0_357:
	s_add_u32 s0, s74, 0x2800000
	s_addc_u32 s1, s75, 0
	v_writelane_b32 v235, s0, 50
	s_barrier
	s_nop 0
	v_writelane_b32 v235, s1, 51
	s_add_u32 s0, s74, 0x2c00000
	s_addc_u32 s1, s75, 0
	v_writelane_b32 v235, s0, 52
	s_nop 1
	v_writelane_b32 v235, s1, 53
	s_add_u32 s0, s74, 0x3000000
	s_addc_u32 s1, s75, 0
	v_writelane_b32 v235, s0, 54
	s_nop 1
	v_writelane_b32 v235, s1, 55
	s_add_u32 s0, s74, 0x3800000
	s_addc_u32 s1, s75, 0
	v_writelane_b32 v235, s0, 56
	s_nop 1
	v_writelane_b32 v235, s1, 57
	s_add_u32 s0, s74, 0x6400000
	s_addc_u32 s1, s75, 0
	v_writelane_b32 v235, s0, 58
	s_nop 1
	v_writelane_b32 v235, s1, 59
	s_add_u32 s0, s74, 0x3b700000
	s_addc_u32 s1, s75, 0
	v_writelane_b32 v235, s0, 60
	s_add_u32 s16, s74, 0x3b800000
	s_addc_u32 s17, s75, 0
	v_writelane_b32 v235, s1, 61
	v_mbcnt_lo_u32_b32 v40, -1, 0
	v_mbcnt_hi_u32_b32 v40, -1, v40
	v_lshrrev_b32_e32 v41, 3, v40
	v_and_b32_e32 v42, 7, v40
	v_readlane_b32 s0, v235, 17
	s_lshl_b32 s1, s0, 14
	v_mul_u32_u24_e32 v43, 33, v41
	v_lshl_add_u32 v43, v42, 2, v43
	v_lshl_add_u32 v160, v43, 2, s1
	v_add_u32_e32 v161, 0x420, v160
	v_add_u32_e32 v162, 0x840, v160
	v_add_u32_e32 v163, 0xc60, v160
	v_add_u32_e32 v164, 0x1080, v160
	v_add_u32_e32 v165, 0x14a0, v160
	v_add_u32_e32 v166, 0x18c0, v160
	v_add_u32_e32 v167, 0x1ce0, v160
	v_mul_u32_u24_e32 v43, 0x108, v42
	v_add_u32_e32 v43, v43, v41
	v_lshl_add_u32 v168, v43, 2, s1
	v_lshlrev_b32_e32 v44, 4, v42
	v_lshl_add_u32 v169, v41, 13, v44
	v_mul_u32_u24_e32 v45, 0xb000, v41
	v_add_u32_e32 v170, v45, v44
	v_lshl_add_u32 v171, v41, 11, v44
	v_lshl_add_u32 v172, v41, 12, v44
	v_mul_u32_u24_e32 v45, 0x2c00, v41
	v_add_u32_e32 v173, v45, v44
	s_lshl_b32 s4, s96, 3
	s_add_i32 s4, s4, s0
	v_readlane_b32 s32, v235, 7
	v_readlane_b32 s33, v235, 8
	v_readlane_b32 s34, v235, 9
	v_readlane_b32 s35, v235, 10
	v_readlane_b32 s40, v235, 11
	v_readlane_b32 s41, v235, 12
	v_readlane_b32 s42, v235, 15
	v_readlane_b32 s43, v235, 16
	v_readlane_b32 s44, v235, 50
	v_readlane_b32 s45, v235, 51
	v_readlane_b32 s46, v235, 52
	v_readlane_b32 s47, v235, 53
	v_readlane_b32 s48, v235, 54
	v_readlane_b32 s49, v235, 55
	v_readlane_b32 s56, v235, 56
	v_readlane_b32 s57, v235, 57
	v_readlane_b32 s6, v235, 58
	v_readlane_b32 s7, v235, 59
.Llw_loop:
	s_cmpk_gt_i32 s4, 0x51ff
	s_cbranch_scc1 .Llw_done
	s_mov_b32 s5, s4
	s_cmpk_lt_i32 s5, 0x400
	s_cbranch_scc0 .Llw_c1
	s_mov_b64 s[66:67], s[32:33]
	s_mov_b64 s[68:69], s[44:45]
	s_movk_i32 s61, 0x800
	s_movk_i32 s62, 0x400
	s_and_b32 s63, s5, 0xffffffc0
	s_and_b32 s64, s5, 63
	s_lshl_b32 s64, s64, 5
	s_mov_b32 s65, s64
	v_mov_b32_e32 v174, v169
	v_mov_b32_e32 v175, v171
	s_branch .Llw_go
.Llw_c1:
	s_addk_i32 s5, 0xfc00
	s_cmpk_lt_i32 s5, 0x400
	s_cbranch_scc0 .Llw_c2
	s_mov_b64 s[66:67], s[34:35]
	s_mov_b64 s[68:69], s[46:47]
	s_movk_i32 s61, 0x800
	s_movk_i32 s62, 0x400
	s_and_b32 s63, s5, 0xffffffc0
	s_and_b32 s64, s5, 63
	s_lshl_b32 s64, s64, 5
	s_mov_b32 s65, s64
	v_mov_b32_e32 v174, v169
	v_mov_b32_e32 v175, v171
	s_branch .Llw_go
.Llw_c2:
	s_addk_i32 s5, 0xfc00
	s_cmpk_lt_i32 s5, 0x800
	s_cbranch_scc0 .Llw_c3
	s_mov_b64 s[66:67], s[40:41]
	s_mov_b64 s[68:69], s[48:49]
	s_movk_i32 s61, 0x800
	s_movk_i32 s62, 0x800
	s_and_b32 s63, s5, 0xffffffc0
	s_and_b32 s64, s5, 63
	s_lshl_b32 s64, s64, 5
	s_mov_b32 s65, s64
	v_mov_b32_e32 v174, v169
	v_mov_b32_e32 v175, v172
	s_branch .Llw_go
.Llw_c3:
	s_addk_i32 s5, 0xf800
	s_cmpk_lt_i32 s5, 0x2c00
	s_cbranch_scc0 .Llw_c4
	s_mov_b64 s[66:67], s[42:43]
	s_mov_b64 s[68:69], s[56:57]
	s_movk_i32 s61, 0x2c00
	s_movk_i32 s62, 0x800
	s_lshr_b32 s2, s5, 5
	s_mulk_i32 s2, 0x1746
	s_lshr_b32 s2, s2, 16
	s_mul_i32 s3, s2, 0x160
	s_sub_i32 s3, s5, s3
	s_lshl_b32 s63, s2, 6
	s_lshl_b32 s64, s3, 5
	s_lshr_b32 s65, s64, 8
	s_lshl_b32 s65, s65, 7
	s_and_b32 s2, s64, 127
	s_add_i32 s65, s65, s2
	s_bitcmp1_b32 s64, 7
	s_cselect_b32 s2, 0x1600, 0
	s_add_i32 s65, s65, s2
	v_mov_b32_e32 v174, v170
	v_mov_b32_e32 v175, v172
	s_branch .Llw_go
.Llw_c4:
	s_addk_i32 s5, 0xd400
	s_mov_b64 s[66:67], s[84:85]
	s_mov_b64 s[68:69], s[6:7]
	s_movk_i32 s61, 0x800
	s_movk_i32 s62, 0x1600
	s_and_b32 s63, s5, 0xffffffc0
	s_and_b32 s64, s5, 63
	s_lshl_b32 s64, s64, 5
	s_mov_b32 s65, s64
	v_mov_b32_e32 v174, v169
	v_mov_b32_e32 v175, v173
.Llw_go:
	s_mul_i32 s2, s63, s61
	s_add_i32 s2, s2, s65
	s_lshl_b32 s2, s2, 2
	s_add_u32 s66, s66, s2
	s_addc_u32 s67, s67, 0
	s_lshl_b32 s70, s61, 5
	global_load_dwordx4 v[76:79], v174, s[66:67]
	s_add_u32 s66, s66, s70
	s_addc_u32 s67, s67, 0
	global_load_dwordx4 v[80:83], v174, s[66:67]
	s_add_u32 s66, s66, s70
	s_addc_u32 s67, s67, 0
	global_load_dwordx4 v[84:87], v174, s[66:67]
	s_add_u32 s66, s66, s70
	s_addc_u32 s67, s67, 0
	global_load_dwordx4 v[88:91], v174, s[66:67]
	s_add_u32 s66, s66, s70
	s_addc_u32 s67, s67, 0
	global_load_dwordx4 v[92:95], v174, s[66:67]
	s_add_u32 s66, s66, s70
	s_addc_u32 s67, s67, 0
	global_load_dwordx4 v[96:99], v174, s[66:67]
	s_add_u32 s66, s66, s70
	s_addc_u32 s67, s67, 0
	global_load_dwordx4 v[100:103], v174, s[66:67]
	s_add_u32 s66, s66, s70
	s_addc_u32 s67, s67, 0
	global_load_dwordx4 v[104:107], v174, s[66:67]
	s_mul_i32 s3, s64, s62
	s_add_i32 s3, s3, s63
	s_lshl_b32 s3, s3, 1
	s_add_u32 s68, s68, s3
	s_addc_u32 s69, s69, 0
	s_lshl_b32 s71, s62, 4
	s_waitcnt vmcnt(7)
	ds_write2_b32 v160, v76, v77 offset1:1
	ds_write2_b32 v160, v78, v79 offset0:2 offset1:3
	s_waitcnt vmcnt(6)
	ds_write2_b32 v161, v80, v81 offset1:1
	ds_write2_b32 v161, v82, v83 offset0:2 offset1:3
	s_waitcnt vmcnt(5)
	ds_write2_b32 v162, v84, v85 offset1:1
	ds_write2_b32 v162, v86, v87 offset0:2 offset1:3
	s_waitcnt vmcnt(4)
	ds_write2_b32 v163, v88, v89 offset1:1
	ds_write2_b32 v163, v90, v91 offset0:2 offset1:3
	s_waitcnt vmcnt(3)
	ds_write2_b32 v164, v92, v93 offset1:1
	ds_write2_b32 v164, v94, v95 offset0:2 offset1:3
	s_waitcnt vmcnt(2)
	ds_write2_b32 v165, v96, v97 offset1:1
	ds_write2_b32 v165, v98, v99 offset0:2 offset1:3
	s_waitcnt vmcnt(1)
	ds_write2_b32 v166, v100, v101 offset1:1
	ds_write2_b32 v166, v102, v103 offset0:2 offset1:3
	s_waitcnt vmcnt(0)
	ds_write2_b32 v167, v104, v105 offset1:1
	ds_write2_b32 v167, v106, v107 offset0:2 offset1:3
	s_waitcnt lgkmcnt(0)
	ds_read2_b32 v[40:41], v168 offset0:0 offset1:8
	ds_read2_b32 v[42:43], v168 offset0:33 offset1:41
	ds_read2_b32 v[44:45], v168 offset0:66 offset1:74
	ds_read2_b32 v[46:47], v168 offset0:99 offset1:107
	ds_read2_b32 v[48:49], v168 offset0:132 offset1:140
	ds_read2_b32 v[50:51], v168 offset0:165 offset1:173
	ds_read2_b32 v[52:53], v168 offset0:198 offset1:206
	ds_read2_b32 v[54:55], v168 offset0:231 offset1:239
	s_waitcnt lgkmcnt(0)
	v_cvt_pk_bf16_f32 v56, v40, v42
	v_cvt_pk_bf16_f32 v57, v44, v46
	v_cvt_pk_bf16_f32 v58, v48, v50
	v_cvt_pk_bf16_f32 v59, v52, v54
	v_cvt_pk_bf16_f32 v60, v41, v43
	v_cvt_pk_bf16_f32 v61, v45, v47
	v_cvt_pk_bf16_f32 v62, v49, v51
	v_cvt_pk_bf16_f32 v63, v53, v55
	global_store_dwordx4 v175, v[56:59], s[68:69]
	s_add_u32 s68, s68, s71
	s_addc_u32 s69, s69, 0
	global_store_dwordx4 v175, v[60:63], s[68:69]
	s_add_u32 s68, s68, s71
	s_addc_u32 s69, s69, 0
	ds_read2_b32 v[40:41], v168 offset0:16 offset1:24
	ds_read2_b32 v[42:43], v168 offset0:49 offset1:57
	ds_read2_b32 v[44:45], v168 offset0:82 offset1:90
	ds_read2_b32 v[46:47], v168 offset0:115 offset1:123
	ds_read2_b32 v[48:49], v168 offset0:148 offset1:156
	ds_read2_b32 v[50:51], v168 offset0:181 offset1:189
	ds_read2_b32 v[52:53], v168 offset0:214 offset1:222
	ds_read2_b32 v[54:55], v168 offset0:247 offset1:255
	s_waitcnt lgkmcnt(0)
	v_cvt_pk_bf16_f32 v56, v40, v42
	v_cvt_pk_bf16_f32 v57, v44, v46
	v_cvt_pk_bf16_f32 v58, v48, v50
	v_cvt_pk_bf16_f32 v59, v52, v54
	v_cvt_pk_bf16_f32 v60, v41, v43
	v_cvt_pk_bf16_f32 v61, v45, v47
	v_cvt_pk_bf16_f32 v62, v49, v51
	v_cvt_pk_bf16_f32 v63, v53, v55
	global_store_dwordx4 v175, v[56:59], s[68:69]
	s_add_u32 s68, s68, s71
	s_addc_u32 s69, s69, 0
	global_store_dwordx4 v175, v[60:63], s[68:69]
	s_add_u32 s68, s68, s71
	s_addc_u32 s69, s69, 0
	s_addk_i32 s4, 0x800
	s_branch .Llw_loop
.Llw_done:
	s_waitcnt vmcnt(0)
	s_barrier
	s_cmp_lt_i32 s96, 32
	s_mov_b64 s[0:1], -1
	v_writelane_b32 v235, s72, 62
	s_nop 1
	v_writelane_b32 v234, s74, 0
	v_writelane_b32 v235, s73, 63
	v_writelane_b32 v234, s75, 1
	s_cbranch_scc0 .LBB0_435
	s_lshr_b32 s0, s92, 31
	s_add_i32 s0, s92, s0
	s_ashr_i32 s56, s0, 1
	s_ashr_i32 s57, s96, 1
	s_bitcmp1_b32 s96, 0
	s_cselect_b64 s[2:3], -1, 0
	s_mov_b64 s[0:1], -1
	s_and_b64 vcc, exec, s[2:3]
	s_cbranch_vccz .LBB0_406
	s_add_u32 s6, s74, 0x3bb00000
	v_readlane_b32 s0, v235, 17
	s_addc_u32 s7, s75, 0
	s_lshl_b32 s0, s0, 5
	s_and_b32 s58, s0, 0x60
	s_lshr_b32 s59, s58, 3
	s_cmp_lt_i32 s57, 16
	s_cselect_b64 s[4:5], -1, 0
	s_cmp_gt_i32 s57, 15
	v_mbcnt_lo_u32_b32 v10, -1, 0
	v_mbcnt_hi_u32_b32 v10, -1, v10
	s_cbranch_scc1 .LBB0_383
	s_ashr_i32 s60, s57, 31
	s_lshr_b32 s0, s60, 29
	s_add_i32 s3, s57, s0
	s_and_b32 s0, s3, -8
	s_sub_i32 s26, s57, s0
	s_cmp_gt_i32 s26, -1
	s_cbranch_scc0 .LBB0_362
	s_lshl_b32 s2, s26, 1
	s_cbranch_execz .LBB0_363
	s_branch .LBB0_364

.LBB0_435:
	s_andn2_b64 vcc, exec, s[0:1]
	s_cbranch_vccnz .LBB0_568
.LBB0_436:
	s_branch .LBB0_568
	s_lshl_b32 s0, s96, 3
	v_readlane_b32 s1, v235, 17
	s_add_i32 s0, s0, s1
	s_add_i32 s8, s0, 0xffffff00
	s_cmpk_gt_i32 s8, 0x51ff
	v_mbcnt_lo_u32_b32 v0, -1, 0
	v_mbcnt_hi_u32_b32 v0, -1, v0
	s_cbranch_scc1 .LBB0_568
	v_readlane_b32 s0, v235, 17
	s_lshl_b32 s0, s0, 14
	v_and_b32_e32 v1, 7, v0
	v_ashrrev_i32_e32 v210, 3, v0
	s_add_i32 s0, s0, 0
	v_lshlrev_b32_e32 v209, 2, v1
	v_lshlrev_b32_e32 v192, 4, v1
	s_movk_i32 s1, 0x84
	v_mul_u32_u24_e32 v0, 0x420, v1
	v_lshlrev_b32_e32 v1, 2, v210
	v_add_u32_e32 v211, s0, v192
	v_mul_lo_u32 v212, v210, s1
	v_add3_u32 v216, s0, v0, v1
	v_readlane_b32 s0, v235, 56
	v_mov_b32_e32 v193, 0
	v_readlane_b32 s1, v235, 57
	v_readlane_b32 s2, v235, 58
	s_add_i32 s9, s88, 0xffffff00
	v_lshl_add_u64 v[196:197], s[0:1], 0, v[192:193]
	v_readlane_b32 s0, v235, 54
	v_readlane_b32 s1, v235, 55
	v_readlane_b32 s3, v235, 59
	s_mov_b32 s7, 0
	v_lshl_add_u64 v[198:199], s[0:1], 0, v[192:193]
	v_readlane_b32 s0, v235, 52
	v_readlane_b32 s1, v235, 53
	v_add_u32_e32 v213, 8, v210
	v_add_u32_e32 v214, 16, v210
	v_lshl_add_u64 v[200:201], s[0:1], 0, v[192:193]
	v_readlane_b32 s0, v235, 50
	v_readlane_b32 s1, v235, 51
	v_add_u32_e32 v215, 24, v210
	v_lshl_add_u64 v[194:195], s[2:3], 0, v[192:193]
	v_lshl_add_u64 v[202:203], s[0:1], 0, v[192:193]
	s_lshl_b32 s10, s8, 5
	s_lshl_b32 s11, s9, 5
	s_movk_i32 s18, 0x7e0
	s_movk_i32 s19, 0x2c00
	s_movk_i32 s20, 0x800
	s_mov_b32 s21, 0xb000
	s_movk_i32 s22, 0x7f8
	s_movk_i32 s23, 0x7f0
	s_movk_i32 s24, 0x7e8
	s_movk_i32 s25, 0x7d8
	s_movk_i32 s26, 0x7d0
	s_movk_i32 s27, 0x7c8
	s_movk_i32 s28, 0x400
	s_movk_i32 s29, 0x3e0
	s_movk_i32 s30, 0x3d8
	s_movk_i32 s31, 0x3d0
	s_movk_i32 s33, 0x3c8
	s_branch .LBB0_441
